# att1 plus loop bookkeeping ahead of end-of-tile barrier and 4-way row-sum add chain
# speedup vs baseline: 1.0077x; 1.0077x over previous
; __device__ __forceinline__ unsigned pk2(float lo, float hi) { f32x2 v = {lo, hi}; bf16x2_t b = __builtin_convertvector(v, bf16x2_t); return __builtin_bit_cast(unsigned, b); }
; template <bool NOSHIFT> __device__ __forceinline__ void diff_attn_unit(LAS unsigned char* lds, bf16_t* proj, const bf16_t* VT, int b, int h, int qb, const AttnConsts ac, const float* gsub, const int tid, bf16_t* obuf, int opitch, int ocol) {
;     ...
;             } else {
; #pragma unroll
;                 for (int mt = 0; mt < 2; ++mt)
; #pragma unroll
;                     for (int r = 0; r < 16; ++r) { const float v = __builtin_amdgcn_exp2f(p[mt][r]); p[mt][r] = v; l += v; }
;             }
;             asm volatile("" ::: "memory");
; #pragma unroll
;             for (int kk = 0; kk < 4; ++kk) { const int mt = kk >> 1, r0 = 8 * (kk & 1); u32x4 w;
;                 w.x = pk2(p[mt][r0], p[mt][r0 + 1]); w.y = pk2(p[mt][r0 + 2], p[mt][r0 + 3]); w.z = pk2(p[mt][r0 + 4], p[mt][r0 + 5]); w.w = pk2(p[mt][r0 + 6], p[mt][r0 + 7]);
;                 pf[kk] = __builtin_bit_cast(bf16x8, w); }
.LBB1_293:
	s_andn2_b64 vcc, exec, s[80:81]
	s_cbranch_vccnz .LBB1_295
	v_add_f32_e32 v7, v207, v96
	v_add_f32_e32 v208, v97, v98
	v_add_f32_e32 v209, v99, v100
	v_add_f32_e32 v210, v101, v102
	v_add_f32_e32 v208, v103, v208
	v_add_f32_e32 v209, v104, v209
	v_add_f32_e32 v210, v105, v210
	v_add_f32_e32 v7, v106, v7
	v_add_f32_e32 v208, v107, v208
	v_add_f32_e32 v209, v108, v209
	v_add_f32_e32 v210, v109, v210
	v_add_f32_e32 v7, v110, v7
	v_add_f32_e32 v208, v111, v208
	v_add_f32_e32 v209, v112, v209
	v_add_f32_e32 v210, v113, v210
	v_add_f32_e32 v7, v114, v7
	v_add_f32_e32 v208, v115, v208
	v_add_f32_e32 v209, v116, v209
	v_add_f32_e32 v210, v117, v210
	v_add_f32_e32 v7, v118, v7
	v_add_f32_e32 v208, v119, v208
	v_add_f32_e32 v209, v120, v209
	v_add_f32_e32 v210, v121, v210
	v_add_f32_e32 v7, v122, v7
	v_add_f32_e32 v208, v123, v208
	v_add_f32_e32 v209, v124, v209
	v_add_f32_e32 v210, v125, v210
	v_add_f32_e32 v7, v126, v7
	v_add_f32_e32 v208, v127, v208
	v_add_f32_e32 v7, v208, v7
	v_add_f32_e32 v209, v210, v209
	v_add_f32_e32 v7, v209, v7
	v_cvt_pk_bf16_f32 v128, v96, v97
	v_cvt_pk_bf16_f32 v129, v98, v99
	v_cvt_pk_bf16_f32 v130, v100, v101
	v_cvt_pk_bf16_f32 v131, v102, v103
	v_cvt_pk_bf16_f32 v100, v104, v105
	v_cvt_pk_bf16_f32 v101, v106, v107
	v_cvt_pk_bf16_f32 v102, v108, v109
	v_cvt_pk_bf16_f32 v103, v110, v111
	v_cvt_pk_bf16_f32 v96, v112, v113
	v_cvt_pk_bf16_f32 v97, v114, v115
	v_cvt_pk_bf16_f32 v98, v116, v117
	v_cvt_pk_bf16_f32 v99, v118, v119
	v_cvt_pk_bf16_f32 v108, v120, v121
	v_cvt_pk_bf16_f32 v109, v122, v123
	v_cvt_pk_bf16_f32 v110, v124, v125
	v_cvt_pk_bf16_f32 v111, v126, v127
	v_mov_b64_e32 v[104:105], v[128:129]
	v_mov_b64_e32 v[106:107], v[130:131]
	s_branch .Latt_cvt_done

; #define ATT_WAITBAR(N) asm volatile("s_waitcnt vmcnt(" #N ") lgkmcnt(0)\n\ts_barrier" ::: "memory")
; template <bool NOSHIFT> __device__ __forceinline__ void diff_attn_unit(LAS unsigned char* lds, bf16_t* proj, const bf16_t* VT, int b, int h, int qb, const AttnConsts ac, const float* gsub, const int tid, bf16_t* obuf, int opitch, int ocol) {
;     ...
;     for (int t = 0; t < NT; ++t) {
;         const int bo = (t & 3) * 16384, sl_cur = bo, sl_prev = ((t - 1) & 3) * 16384;
;         if (t + 2 < NT) ATT_ISSUE(t + 2);
;         const int kv0 = 64 * t;
;     ...
;         if (t + 2 < NT) ATT_WAITBAR(4); else ATT_WAITBAR(0);
.LBB1_298:
	s_add_i32 s82, s82, 1
	s_add_i32 s47, s47, 64
	v_lshl_add_u64 v[2:3], v[2:3], 0, s[90:91]
	v_lshl_add_u64 v[4:5], v[4:5], 0, s[50:51]
	v_subrev_u32_e32 v0, 64, v0
	v_mov_b32_e32 v207, v7
	s_and_b64 vcc, exec, s[78:79]
	s_cbranch_vccz .Latt_wb4
	s_waitcnt vmcnt(0) lgkmcnt(0)
	s_barrier
	s_branch .Latt_wbdone

; #define ATT_WAITBAR(N) asm volatile("s_waitcnt vmcnt(" #N ") lgkmcnt(0)\n\ts_barrier" ::: "memory")
; template <bool NOSHIFT> __device__ __forceinline__ void diff_attn_unit(LAS unsigned char* lds, bf16_t* proj, const bf16_t* VT, int b, int h, int qb, const AttnConsts ac, const float* gsub, const int tid, bf16_t* obuf, int opitch, int ocol) {
;     ...
;     for (int t = 0; t < NT; ++t) {
;         const int bo = (t & 3) * 16384, sl_cur = bo, sl_prev = ((t - 1) & 3) * 16384;
;         if (t + 2 < NT) ATT_ISSUE(t + 2);
;     ...
;         if (t + 2 < NT) ATT_WAITBAR(4); else ATT_WAITBAR(0);
.Latt_wbdone:
	s_cmp_eq_u32 s57, s14
	s_cbranch_scc1 .LBB1_304
	s_cmp_ge_u32 s82, s45
	s_cselect_b64 s[78:79], -1, 0
	s_and_b64 vcc, exec, s[78:79]
	s_cbranch_vccz .LBB1_287
	s_branch .LBB1_288
